# m13 + final LayerNorm (second pass): each 64-column block stores its f32 rows as soon as it is normalised instead of one 64 MB store burst after the loop (overlap drain with normalisation)
# speedup vs baseline: 1.0055x; 1.0055x over previous
.LBB0_578:
	v_lshl_add_u32 v188, v200, 3, 0
	s_waitcnt lgkmcnt(0)
	v_cmp_ne_u32_e32 vcc, 0, v162
	ds_read_b64 v[162:163], v188 offset:8192
	s_or_b64 s[40:41], vcc, s[58:59]
	s_cmp_eq_u64 s[40:41], 0
	s_cselect_b64 s[100:101], s[38:39], 0
	v_add_u32_e32 v174, s24, v200
	s_add_u32 s0, s56, 0x3400000
	v_ashrrev_i32_e32 v175, 31, v174
	s_waitcnt lgkmcnt(0)
	v_sub_f32_e32 v69, v69, v162
	v_sub_f32_e32 v68, v68, v162
	v_sub_f32_e32 v67, v67, v162
	v_sub_f32_e32 v66, v66, v162
	s_addc_u32 s1, s57, 0
	v_lshlrev_b64 v[166:167], 10, v[174:175]
	v_pk_mul_f32 v[66:67], v[162:163], v[66:67] op_sel:[1,0]
	v_pk_mul_f32 v[68:69], v[162:163], v[68:69] op_sel:[1,0]
	s_waitcnt vmcnt(0)
	v_pk_fma_f32 v[162:163], v[130:131], v[66:67], v[134:135]
	v_pk_fma_f32 v[164:165], v[132:133], v[68:69], v[136:137]
	s_and_b64 vcc, exec, s[38:39]
	v_lshl_add_u64 v[176:177], v[166:167], 1, s[0:1]
	s_cbranch_vccnz .LBB0_580
	v_pk_fma_f32 v[66:67], v[172:173], v[164:165], v[140:141]
	v_pk_fma_f32 v[68:69], v[170:171], v[162:163], v[138:139]
	s_nop 0
	v_cvt_pk_bf16_f32 v68, v68, v69
	v_cvt_pk_bf16_f32 v66, v66, v67
	s_nop 0
	v_cndmask_b32_e64 v67, v66, v221, s[40:41]
	v_cndmask_b32_e64 v66, v68, v221, s[40:41]
	v_lshl_add_u64 v[68:69], v[160:161], 1, v[176:177]
	global_store_dwordx2 v[68:69], v[66:67], off

.LBB0_594:
	s_and_b64 vcc, exec, s[100:101]
	s_cbranch_vccz .Lef_skip0
	v_lshlrev_b64 v[230:231], 10, v[144:145]
	v_lshl_add_u64 v[230:231], v[230:231], 2, s[52:53]
	v_lshl_add_u64 v[230:231], v[230:231], 0, v[142:143]
	global_store_dwordx4 v[230:231], v[162:165], off
	v_lshlrev_b64 v[236:237], 10, v[146:147]
	v_lshl_add_u64 v[236:237], v[236:237], 2, s[52:53]
	v_lshl_add_u64 v[236:237], v[236:237], 0, v[142:143]
	global_store_dwordx4 v[236:237], v[166:169], off
	v_lshlrev_b64 v[230:231], 10, v[148:149]
	v_lshl_add_u64 v[230:231], v[230:231], 2, s[52:53]
	v_lshl_add_u64 v[230:231], v[230:231], 0, v[142:143]
	global_store_dwordx4 v[230:231], v[106:109], off
	v_lshlrev_b64 v[236:237], 10, v[150:151]
	v_lshl_add_u64 v[236:237], v[236:237], 2, s[52:53]
	v_lshl_add_u64 v[236:237], v[236:237], 0, v[142:143]
	global_store_dwordx4 v[236:237], v[118:121], off
	v_lshlrev_b64 v[230:231], 10, v[152:153]
	v_lshl_add_u64 v[230:231], v[230:231], 2, s[52:53]
	v_lshl_add_u64 v[230:231], v[230:231], 0, v[142:143]
	global_store_dwordx4 v[230:231], v[126:129], off
	v_lshlrev_b64 v[236:237], 10, v[154:155]
	v_lshl_add_u64 v[236:237], v[236:237], 2, s[52:53]
	v_lshl_add_u64 v[236:237], v[236:237], 0, v[142:143]
	global_store_dwordx4 v[236:237], v[122:125], off
	v_lshlrev_b64 v[230:231], 10, v[156:157]
	v_lshl_add_u64 v[230:231], v[230:231], 2, s[52:53]
	v_lshl_add_u64 v[230:231], v[230:231], 0, v[142:143]
	global_store_dwordx4 v[230:231], v[110:113], off
	v_lshlrev_b64 v[236:237], 10, v[158:159]
	v_lshl_add_u64 v[236:237], v[236:237], 2, s[52:53]
	v_lshl_add_u64 v[236:237], v[236:237], 0, v[142:143]
	global_store_dwordx4 v[236:237], v[130:133], off

.LBB0_612:
	s_and_b64 vcc, exec, s[100:101]
	s_cbranch_vccz .Lef_skip1
	v_lshlrev_b64 v[230:231], 10, v[144:145]
	v_lshl_add_u64 v[230:231], v[230:231], 2, s[52:53]
	v_lshl_add_u64 v[230:231], v[230:231], 0, v[142:143]
	v_mov_b64_e32 v[226:227], v[138:139]
	v_mov_b64_e32 v[228:229], v[134:135]
	global_store_dwordx4 v[230:231], v[226:229], off offset:64
	v_lshlrev_b64 v[236:237], 10, v[146:147]
	v_lshl_add_u64 v[236:237], v[236:237], 2, s[52:53]
	v_lshl_add_u64 v[236:237], v[236:237], 0, v[142:143]
	v_mov_b64_e32 v[232:233], v[140:141]
	v_mov_b64_e32 v[234:235], v[136:137]
	global_store_dwordx4 v[236:237], v[232:235], off offset:64
	v_lshlrev_b64 v[230:231], 10, v[148:149]
	v_lshl_add_u64 v[230:231], v[230:231], 2, s[52:53]
	v_lshl_add_u64 v[230:231], v[230:231], 0, v[142:143]
	v_mov_b64_e32 v[226:227], v[172:173]
	v_mov_b64_e32 v[228:229], v[170:171]
	global_store_dwordx4 v[230:231], v[226:229], off offset:64
	v_lshlrev_b64 v[236:237], 10, v[150:151]
	v_lshl_add_u64 v[236:237], v[236:237], 2, s[52:53]
	v_lshl_add_u64 v[236:237], v[236:237], 0, v[142:143]
	v_mov_b64_e32 v[232:233], v[76:77]
	v_mov_b64_e32 v[234:235], v[74:75]
	global_store_dwordx4 v[236:237], v[232:235], off offset:64
	v_lshlrev_b64 v[230:231], 10, v[152:153]
	v_lshl_add_u64 v[230:231], v[230:231], 2, s[52:53]
	v_lshl_add_u64 v[230:231], v[230:231], 0, v[142:143]
	v_mov_b64_e32 v[226:227], v[174:175]
	v_mov_b64_e32 v[228:229], v[98:99]
	global_store_dwordx4 v[230:231], v[226:229], off offset:64
	v_lshlrev_b64 v[236:237], 10, v[154:155]
	v_lshl_add_u64 v[236:237], v[236:237], 2, s[52:53]
	v_lshl_add_u64 v[236:237], v[236:237], 0, v[142:143]
	v_mov_b64_e32 v[232:233], v[114:115]
	v_mov_b64_e32 v[234:235], v[100:101]
	global_store_dwordx4 v[236:237], v[232:235], off offset:64
	v_lshlrev_b64 v[230:231], 10, v[156:157]
	v_lshl_add_u64 v[230:231], v[230:231], 2, s[52:53]
	v_lshl_add_u64 v[230:231], v[230:231], 0, v[142:143]
	v_mov_b64_e32 v[226:227], v[104:105]
	v_mov_b64_e32 v[228:229], v[102:103]
	global_store_dwordx4 v[230:231], v[226:229], off offset:64
	v_lshlrev_b64 v[236:237], 10, v[158:159]
	v_lshl_add_u64 v[236:237], v[236:237], 2, s[52:53]
	v_lshl_add_u64 v[236:237], v[236:237], 0, v[142:143]
	global_store_dwordx4 v[236:237], v[66:69], off offset:64

.LBB0_630:
	s_and_b64 vcc, exec, s[100:101]
	s_cbranch_vccz .Lef_skip2
	v_lshlrev_b64 v[230:231], 10, v[144:145]
	v_lshl_add_u64 v[230:231], v[230:231], 2, s[52:53]
	v_lshl_add_u64 v[230:231], v[230:231], 0, v[142:143]
	v_mov_b64_e32 v[226:227], v[90:91]
	v_mov_b64_e32 v[228:229], v[78:79]
	global_store_dwordx4 v[230:231], v[226:229], off offset:512
	v_lshlrev_b64 v[236:237], 10, v[146:147]
	v_lshl_add_u64 v[236:237], v[236:237], 2, s[52:53]
	v_lshl_add_u64 v[236:237], v[236:237], 0, v[142:143]
	v_mov_b64_e32 v[232:233], v[92:93]
	v_mov_b64_e32 v[234:235], v[80:81]
	global_store_dwordx4 v[236:237], v[232:235], off offset:512
	v_lshlrev_b64 v[230:231], 10, v[148:149]
	v_lshl_add_u64 v[230:231], v[230:231], 2, s[52:53]
	v_lshl_add_u64 v[230:231], v[230:231], 0, v[142:143]
	v_mov_b64_e32 v[226:227], v[96:97]
	v_mov_b64_e32 v[228:229], v[94:95]
	global_store_dwordx4 v[230:231], v[226:229], off offset:512
	v_lshlrev_b64 v[236:237], 10, v[150:151]
	v_lshl_add_u64 v[236:237], v[236:237], 2, s[52:53]
	v_lshl_add_u64 v[236:237], v[236:237], 0, v[142:143]
	v_mov_b64_e32 v[232:233], v[44:45]
	v_mov_b64_e32 v[234:235], v[42:43]
	global_store_dwordx4 v[236:237], v[232:235], off offset:512
	v_lshlrev_b64 v[230:231], 10, v[152:153]
	v_lshl_add_u64 v[230:231], v[230:231], 2, s[52:53]
	v_lshl_add_u64 v[230:231], v[230:231], 0, v[142:143]
	v_mov_b64_e32 v[226:227], v[116:117]
	v_mov_b64_e32 v[228:229], v[58:59]
	global_store_dwordx4 v[230:231], v[226:229], off offset:512
	v_lshlrev_b64 v[236:237], 10, v[154:155]
	v_lshl_add_u64 v[236:237], v[236:237], 2, s[52:53]
	v_lshl_add_u64 v[236:237], v[236:237], 0, v[142:143]
	v_mov_b64_e32 v[232:233], v[70:71]
	v_mov_b64_e32 v[234:235], v[60:61]
	global_store_dwordx4 v[236:237], v[232:235], off offset:512
	v_lshlrev_b64 v[230:231], 10, v[156:157]
	v_lshl_add_u64 v[230:231], v[230:231], 2, s[52:53]
	v_lshl_add_u64 v[230:231], v[230:231], 0, v[142:143]
	v_mov_b64_e32 v[226:227], v[86:87]
	v_mov_b64_e32 v[228:229], v[72:73]
	global_store_dwordx4 v[230:231], v[226:229], off offset:512
	v_lshlrev_b64 v[236:237], 10, v[158:159]
	v_lshl_add_u64 v[236:237], v[236:237], 2, s[52:53]
	v_lshl_add_u64 v[236:237], v[236:237], 0, v[142:143]
	global_store_dwordx4 v[236:237], v[34:37], off offset:512

.LBB0_650:
	s_and_b64 vcc, exec, s[100:101]
	s_cbranch_vccz .Lef_skip3
	v_lshlrev_b64 v[230:231], 10, v[144:145]
	v_lshl_add_u64 v[230:231], v[230:231], 2, s[52:53]
	v_lshl_add_u64 v[230:231], v[230:231], 0, v[142:143]
	v_mov_b64_e32 v[226:227], v[46:47]
	v_mov_b64_e32 v[228:229], v[2:3]
	global_store_dwordx4 v[230:231], v[226:229], off offset:576
	v_lshlrev_b64 v[236:237], 10, v[146:147]
	v_lshl_add_u64 v[236:237], v[236:237], 2, s[52:53]
	v_lshl_add_u64 v[236:237], v[236:237], 0, v[142:143]
	v_mov_b64_e32 v[232:233], v[6:7]
	v_mov_b64_e32 v[234:235], v[4:5]
	global_store_dwordx4 v[236:237], v[232:235], off offset:576
	v_lshlrev_b64 v[230:231], 10, v[148:149]
	v_lshl_add_u64 v[230:231], v[230:231], 2, s[52:53]
	v_lshl_add_u64 v[230:231], v[230:231], 0, v[142:143]
	v_mov_b64_e32 v[226:227], v[12:13]
	v_mov_b64_e32 v[228:229], v[8:9]
	global_store_dwordx4 v[230:231], v[226:229], off offset:576
	v_lshlrev_b64 v[236:237], 10, v[150:151]
	v_lshl_add_u64 v[236:237], v[236:237], 2, s[52:53]
	v_lshl_add_u64 v[236:237], v[236:237], 0, v[142:143]
	v_mov_b64_e32 v[232:233], v[18:19]
	v_mov_b64_e32 v[234:235], v[10:11]
	global_store_dwordx4 v[236:237], v[232:235], off offset:576
	v_lshlrev_b64 v[230:231], 10, v[152:153]
	v_lshl_add_u64 v[230:231], v[230:231], 2, s[52:53]
	v_lshl_add_u64 v[230:231], v[230:231], 0, v[142:143]
	v_mov_b64_e32 v[226:227], v[28:29]
	v_mov_b64_e32 v[228:229], v[20:21]
	global_store_dwordx4 v[230:231], v[226:229], off offset:576
	v_lshlrev_b64 v[236:237], 10, v[154:155]
	v_lshl_add_u64 v[236:237], v[236:237], 2, s[52:53]
	v_lshl_add_u64 v[236:237], v[236:237], 0, v[142:143]
	v_mov_b64_e32 v[232:233], v[38:39]
	v_mov_b64_e32 v[234:235], v[26:27]
	global_store_dwordx4 v[236:237], v[232:235], off offset:576
	v_lshlrev_b64 v[230:231], 10, v[156:157]
	v_lshl_add_u64 v[230:231], v[230:231], 2, s[52:53]
	v_lshl_add_u64 v[230:231], v[230:231], 0, v[142:143]
	v_mov_b64_e32 v[226:227], v[48:49]
	v_mov_b64_e32 v[228:229], v[40:41]
	global_store_dwordx4 v[230:231], v[226:229], off offset:576
	v_lshlrev_b64 v[236:237], 10, v[158:159]
	v_lshl_add_u64 v[236:237], v[236:237], 2, s[52:53]
	v_lshl_add_u64 v[236:237], v[236:237], 0, v[142:143]
	global_store_dwordx4 v[236:237], v[14:17], off offset:576

.LBB0_734:
	s_and_b64 vcc, exec, s[100:101]
	s_cbranch_vccnz .LBB0_735
	v_lshlrev_b64 v[24:25], 10, v[144:145]
	v_lshl_add_u64 v[24:25], v[24:25], 2, s[52:53]
	v_cndmask_b32_e64 v33, v165, v222, s[40:41]
	v_cndmask_b32_e64 v32, v164, v222, s[40:41]
	v_cndmask_b32_e64 v31, v163, v222, s[40:41]
	v_cndmask_b32_e64 v30, v162, v222, s[40:41]
	v_lshl_add_u64 v[24:25], v[24:25], 0, v[142:143]
	global_store_dwordx4 v[24:25], v[30:33], off
	v_lshlrev_b64 v[50:51], 10, v[146:147]
	v_lshlrev_b64 v[52:53], 10, v[148:149]
	v_cndmask_b32_e64 v33, v135, v222, s[40:41]
	v_cndmask_b32_e64 v32, v134, v222, s[40:41]
	v_cndmask_b32_e64 v31, v139, v222, s[40:41]
	v_cndmask_b32_e64 v30, v138, v222, s[40:41]
	global_store_dwordx4 v[24:25], v[30:33], off offset:64
	v_cndmask_b32_e64 v5, v5, v222, s[40:41]
	v_cndmask_b32_e64 v4, v4, v222, s[40:41]
	v_cndmask_b32_e64 v33, v79, v222, s[40:41]
	v_cndmask_b32_e64 v32, v78, v222, s[40:41]
	v_cndmask_b32_e64 v31, v91, v222, s[40:41]
	v_cndmask_b32_e64 v30, v90, v222, s[40:41]
	global_store_dwordx4 v[24:25], v[30:33], off offset:512
	v_lshlrev_b64 v[54:55], 10, v[150:151]
	v_lshlrev_b64 v[56:57], 10, v[152:153]
	v_cndmask_b32_e64 v33, v3, v222, s[40:41]
	v_cndmask_b32_e64 v32, v2, v222, s[40:41]
	v_cndmask_b32_e64 v31, v47, v222, s[40:41]
	v_cndmask_b32_e64 v30, v46, v222, s[40:41]
	v_lshl_add_u64 v[2:3], v[50:51], 2, s[52:53]
	global_store_dwordx4 v[24:25], v[30:33], off offset:576
	v_lshl_add_u64 v[24:25], v[2:3], 0, v[142:143]
	v_cndmask_b32_e64 v3, v7, v222, s[40:41]
	v_cndmask_b32_e64 v2, v6, v222, s[40:41]
	v_lshl_add_u64 v[6:7], v[52:53], 2, s[52:53]
	global_store_dwordx4 v[24:25], v[2:5], off offset:576
	v_lshl_add_u64 v[6:7], v[6:7], 0, v[142:143]
	v_lshlrev_b64 v[62:63], 10, v[154:155]
	v_cndmask_b32_e64 v5, v109, v222, s[40:41]
	v_cndmask_b32_e64 v4, v108, v222, s[40:41]
	v_cndmask_b32_e64 v3, v107, v222, s[40:41]
	v_cndmask_b32_e64 v2, v106, v222, s[40:41]
	global_store_dwordx4 v[6:7], v[2:5], off
	v_lshlrev_b64 v[64:65], 10, v[156:157]
	v_lshlrev_b64 v[22:23], 10, v[158:159]
	v_cndmask_b32_e64 v5, v171, v222, s[40:41]
	v_cndmask_b32_e64 v4, v170, v222, s[40:41]
	v_cndmask_b32_e64 v3, v173, v222, s[40:41]
	v_cndmask_b32_e64 v2, v172, v222, s[40:41]
	global_store_dwordx4 v[6:7], v[2:5], off offset:64
	v_cndmask_b32_e64 v33, v169, v222, s[40:41]
	v_cndmask_b32_e64 v32, v168, v222, s[40:41]
	v_cndmask_b32_e64 v5, v95, v222, s[40:41]
	v_cndmask_b32_e64 v4, v94, v222, s[40:41]
	v_cndmask_b32_e64 v3, v97, v222, s[40:41]
	v_cndmask_b32_e64 v2, v96, v222, s[40:41]
	global_store_dwordx4 v[6:7], v[2:5], off offset:512
	v_cndmask_b32_e64 v31, v167, v222, s[40:41]
	v_cndmask_b32_e64 v30, v166, v222, s[40:41]
	v_cndmask_b32_e64 v5, v9, v222, s[40:41]
	v_cndmask_b32_e64 v4, v8, v222, s[40:41]
	v_cndmask_b32_e64 v3, v13, v222, s[40:41]
	v_cndmask_b32_e64 v2, v12, v222, s[40:41]
	global_store_dwordx4 v[6:7], v[2:5], off offset:576
	v_lshl_add_u64 v[6:7], v[54:55], 2, s[52:53]
	v_lshl_add_u64 v[6:7], v[6:7], 0, v[142:143]
	v_cndmask_b32_e64 v5, v121, v222, s[40:41]
	v_cndmask_b32_e64 v4, v120, v222, s[40:41]
	v_cndmask_b32_e64 v3, v119, v222, s[40:41]
	v_cndmask_b32_e64 v2, v118, v222, s[40:41]
	global_store_dwordx4 v[6:7], v[2:5], off
	global_store_dwordx4 v[24:25], v[30:33], off
	s_nop 0
	v_cndmask_b32_e64 v5, v75, v222, s[40:41]
	v_cndmask_b32_e64 v4, v74, v222, s[40:41]
	v_cndmask_b32_e64 v3, v77, v222, s[40:41]
	v_cndmask_b32_e64 v2, v76, v222, s[40:41]
	global_store_dwordx4 v[6:7], v[2:5], off offset:64
	v_cndmask_b32_e64 v33, v137, v222, s[40:41]
	v_cndmask_b32_e64 v32, v136, v222, s[40:41]
	v_cndmask_b32_e64 v5, v43, v222, s[40:41]
	v_cndmask_b32_e64 v4, v42, v222, s[40:41]
	v_cndmask_b32_e64 v3, v45, v222, s[40:41]
	v_cndmask_b32_e64 v2, v44, v222, s[40:41]
	global_store_dwordx4 v[6:7], v[2:5], off offset:512
	v_cndmask_b32_e64 v31, v141, v222, s[40:41]
	v_cndmask_b32_e64 v30, v140, v222, s[40:41]
	v_cndmask_b32_e64 v5, v11, v222, s[40:41]
	v_cndmask_b32_e64 v4, v10, v222, s[40:41]
	v_cndmask_b32_e64 v3, v19, v222, s[40:41]
	v_cndmask_b32_e64 v2, v18, v222, s[40:41]
	global_store_dwordx4 v[6:7], v[2:5], off offset:576
	v_lshl_add_u64 v[6:7], v[56:57], 2, s[52:53]
	v_lshl_add_u64 v[6:7], v[6:7], 0, v[142:143]
	v_cndmask_b32_e64 v5, v129, v222, s[40:41]
	v_cndmask_b32_e64 v4, v128, v222, s[40:41]
	v_cndmask_b32_e64 v3, v127, v222, s[40:41]
	v_cndmask_b32_e64 v2, v126, v222, s[40:41]
	global_store_dwordx4 v[6:7], v[2:5], off
	global_store_dwordx4 v[24:25], v[30:33], off offset:64
	s_nop 0
	v_cndmask_b32_e64 v5, v99, v222, s[40:41]
	v_cndmask_b32_e64 v4, v98, v222, s[40:41]
	v_cndmask_b32_e64 v3, v175, v222, s[40:41]
	v_cndmask_b32_e64 v2, v174, v222, s[40:41]
	global_store_dwordx4 v[6:7], v[2:5], off offset:64
	v_cndmask_b32_e64 v33, v81, v222, s[40:41]
	v_cndmask_b32_e64 v32, v80, v222, s[40:41]
	v_cndmask_b32_e64 v5, v59, v222, s[40:41]
	v_cndmask_b32_e64 v4, v58, v222, s[40:41]
	v_cndmask_b32_e64 v3, v117, v222, s[40:41]
	v_cndmask_b32_e64 v2, v116, v222, s[40:41]
	global_store_dwordx4 v[6:7], v[2:5], off offset:512
	v_cndmask_b32_e64 v31, v93, v222, s[40:41]
	v_cndmask_b32_e64 v30, v92, v222, s[40:41]
	v_cndmask_b32_e64 v5, v21, v222, s[40:41]
	v_cndmask_b32_e64 v4, v20, v222, s[40:41]
	v_cndmask_b32_e64 v3, v29, v222, s[40:41]
	v_cndmask_b32_e64 v2, v28, v222, s[40:41]
	global_store_dwordx4 v[6:7], v[2:5], off offset:576
	v_lshl_add_u64 v[6:7], v[62:63], 2, s[52:53]
	v_lshl_add_u64 v[6:7], v[6:7], 0, v[142:143]
	v_cndmask_b32_e64 v5, v125, v222, s[40:41]
	v_cndmask_b32_e64 v4, v124, v222, s[40:41]
	v_cndmask_b32_e64 v3, v123, v222, s[40:41]
	v_cndmask_b32_e64 v2, v122, v222, s[40:41]
	global_store_dwordx4 v[6:7], v[2:5], off
	global_store_dwordx4 v[24:25], v[30:33], off offset:512
	s_nop 0
	v_cndmask_b32_e64 v5, v101, v222, s[40:41]
	v_cndmask_b32_e64 v4, v100, v222, s[40:41]
	v_cndmask_b32_e64 v3, v115, v222, s[40:41]
	v_cndmask_b32_e64 v2, v114, v222, s[40:41]
	global_store_dwordx4 v[6:7], v[2:5], off offset:64
	s_nop 1
	v_cndmask_b32_e64 v5, v61, v222, s[40:41]
	v_cndmask_b32_e64 v4, v60, v222, s[40:41]
	v_cndmask_b32_e64 v3, v71, v222, s[40:41]
	v_cndmask_b32_e64 v2, v70, v222, s[40:41]
	global_store_dwordx4 v[6:7], v[2:5], off offset:512
	s_nop 1
	v_cndmask_b32_e64 v5, v27, v222, s[40:41]
	v_cndmask_b32_e64 v4, v26, v222, s[40:41]
	v_cndmask_b32_e64 v3, v39, v222, s[40:41]
	v_cndmask_b32_e64 v2, v38, v222, s[40:41]
	global_store_dwordx4 v[6:7], v[2:5], off offset:576
	v_lshl_add_u64 v[6:7], v[64:65], 2, s[52:53]
	v_lshl_add_u64 v[6:7], v[6:7], 0, v[142:143]
	v_cndmask_b32_e64 v5, v113, v222, s[40:41]
	v_cndmask_b32_e64 v4, v112, v222, s[40:41]
	v_cndmask_b32_e64 v3, v111, v222, s[40:41]
	v_cndmask_b32_e64 v2, v110, v222, s[40:41]
	global_store_dwordx4 v[6:7], v[2:5], off
	s_nop 1
	v_cndmask_b32_e64 v5, v103, v222, s[40:41]
	v_cndmask_b32_e64 v4, v102, v222, s[40:41]
	v_cndmask_b32_e64 v3, v105, v222, s[40:41]
	v_cndmask_b32_e64 v2, v104, v222, s[40:41]
	global_store_dwordx4 v[6:7], v[2:5], off offset:64
	s_nop 1
	v_cndmask_b32_e64 v5, v73, v222, s[40:41]
	v_cndmask_b32_e64 v4, v72, v222, s[40:41]
	v_cndmask_b32_e64 v3, v87, v222, s[40:41]
	v_cndmask_b32_e64 v2, v86, v222, s[40:41]
	global_store_dwordx4 v[6:7], v[2:5], off offset:512
	s_nop 1
	v_cndmask_b32_e64 v5, v41, v222, s[40:41]
	v_cndmask_b32_e64 v4, v40, v222, s[40:41]
	v_cndmask_b32_e64 v3, v49, v222, s[40:41]
	v_cndmask_b32_e64 v2, v48, v222, s[40:41]
	global_store_dwordx4 v[6:7], v[2:5], off offset:576
	v_lshl_add_u64 v[6:7], v[22:23], 2, s[52:53]
	v_lshl_add_u64 v[6:7], v[6:7], 0, v[142:143]
	v_cndmask_b32_e64 v5, v133, v222, s[40:41]
	v_cndmask_b32_e64 v4, v132, v222, s[40:41]
	v_cndmask_b32_e64 v3, v131, v222, s[40:41]
	v_cndmask_b32_e64 v2, v130, v222, s[40:41]
	global_store_dwordx4 v[6:7], v[2:5], off
	s_nop 1
	v_cndmask_b32_e64 v5, v69, v222, s[40:41]
	v_cndmask_b32_e64 v4, v68, v222, s[40:41]
	v_cndmask_b32_e64 v3, v67, v222, s[40:41]
	v_cndmask_b32_e64 v2, v66, v222, s[40:41]
	global_store_dwordx4 v[6:7], v[2:5], off offset:64
	s_nop 1
	v_cndmask_b32_e64 v5, v37, v222, s[40:41]
	v_cndmask_b32_e64 v4, v36, v222, s[40:41]
	v_cndmask_b32_e64 v3, v35, v222, s[40:41]
	v_cndmask_b32_e64 v2, v34, v222, s[40:41]
	global_store_dwordx4 v[6:7], v[2:5], off offset:512
	s_nop 1
	v_cndmask_b32_e64 v5, v17, v222, s[40:41]
	v_cndmask_b32_e64 v4, v16, v222, s[40:41]
	v_cndmask_b32_e64 v3, v15, v222, s[40:41]
	v_cndmask_b32_e64 v2, v14, v222, s[40:41]
	global_store_dwordx4 v[6:7], v[2:5], off offset:576

	.amdhsa_kernel _Z8mega_fwd4Args
		.amdhsa_group_segment_fixed_size 0
		.amdhsa_private_segment_fixed_size 0
		.amdhsa_kernarg_size 432
		.amdhsa_user_sgpr_count 2
		.amdhsa_user_sgpr_dispatch_ptr 0
		.amdhsa_user_sgpr_queue_ptr 0
		.amdhsa_user_sgpr_kernarg_segment_ptr 1
		.amdhsa_user_sgpr_dispatch_id 0
		.amdhsa_user_sgpr_kernarg_preload_length 0
		.amdhsa_user_sgpr_kernarg_preload_offset 0
		.amdhsa_user_sgpr_private_segment_size 0
		.amdhsa_uses_dynamic_stack 0
		.amdhsa_enable_private_segment 0
		.amdhsa_system_sgpr_workgroup_id_x 1
		.amdhsa_system_sgpr_workgroup_id_y 0
		.amdhsa_system_sgpr_workgroup_id_z 0
		.amdhsa_system_sgpr_workgroup_info 0
		.amdhsa_system_vgpr_workitem_id 0
		.amdhsa_next_free_vgpr 254
		.amdhsa_next_free_sgpr 102
		.amdhsa_accum_offset 256
		.amdhsa_reserve_vcc 1
		.amdhsa_float_round_mode_32 0
		.amdhsa_float_round_mode_16_64 0
		.amdhsa_float_denorm_mode_32 3
		.amdhsa_float_denorm_mode_16_64 3
		.amdhsa_dx10_clamp 1
		.amdhsa_ieee_mode 1
		.amdhsa_fp16_overflow 0
		.amdhsa_tg_split 0
		.amdhsa_exception_fp_ieee_invalid_op 0
		.amdhsa_exception_fp_denorm_src 0
		.amdhsa_exception_fp_ieee_div_zero 0
		.amdhsa_exception_fp_ieee_overflow 0
		.amdhsa_exception_fp_ieee_underflow 0
		.amdhsa_exception_fp_ieee_inexact 0
		.amdhsa_exception_int_div_zero 0
	.end_amdhsa_kernel

.Lfunc_end0:
	.size	_Z8mega_fwd4Args, .Lfunc_end0-_Z8mega_fwd4Args
	.set _Z8mega_fwd4Args.num_vgpr, 254
	.set _Z8mega_fwd4Args.num_agpr, 0
	.set _Z8mega_fwd4Args.numbered_sgpr, 102
	.set _Z8mega_fwd4Args.num_named_barrier, 0
	.set _Z8mega_fwd4Args.private_seg_size, 0
	.set _Z8mega_fwd4Args.uses_vcc, 1
	.set _Z8mega_fwd4Args.uses_flat_scratch, 0
	.set _Z8mega_fwd4Args.has_dyn_sized_stack, 0
	.set _Z8mega_fwd4Args.has_recursion, 0
	.set _Z8mega_fwd4Args.has_indirect_call, 0

amdhsa.kernels:
  - .agpr_count:     0
    .args:
      - .offset:         0
        .size:           176
        .value_kind:     by_value
      - .offset:         176
        .size:           4
        .value_kind:     hidden_block_count_x
      - .offset:         180
        .size:           4
        .value_kind:     hidden_block_count_y
      - .offset:         184
        .size:           4
        .value_kind:     hidden_block_count_z
      - .offset:         188
        .size:           2
        .value_kind:     hidden_group_size_x
      - .offset:         190
        .size:           2
        .value_kind:     hidden_group_size_y
      - .offset:         192
        .size:           2
        .value_kind:     hidden_group_size_z
      - .offset:         194
        .size:           2
        .value_kind:     hidden_remainder_x
      - .offset:         196
        .size:           2
        .value_kind:     hidden_remainder_y
      - .offset:         198
        .size:           2
        .value_kind:     hidden_remainder_z
      - .offset:         216
        .size:           8
        .value_kind:     hidden_global_offset_x
      - .offset:         224
        .size:           8
        .value_kind:     hidden_global_offset_y
      - .offset:         232
        .size:           8
        .value_kind:     hidden_global_offset_z
      - .offset:         240
        .size:           2
        .value_kind:     hidden_grid_dims
      - .offset:         296
        .size:           4
        .value_kind:     hidden_dynamic_lds_size
    .group_segment_fixed_size: 0
    .kernarg_segment_align: 8
    .kernarg_segment_size: 432
    .language:       OpenCL C
    .language_version:
      - 2
      - 0
    .max_flat_workgroup_size: 512
    .name:           _Z8mega_fwd4Args
    .private_segment_fixed_size: 0
    .sgpr_count:     108
    .sgpr_spill_count: 182
    .symbol:         _Z8mega_fwd4Args.kd
    .uniform_work_group_size: 1
    .uses_dynamic_stack: false
    .vgpr_count:     254
    .vgpr_spill_count: 0
    .wavefront_size: 64
